# v121: issue first v[232:235]-group MFMA two slots earlier in both LRU gate loops so s_nop 7 becomes s_nop 5 under MFMA shadow (reschedule only)
# speedup vs baseline: 1.0051x; 1.0051x over previous
.LBB0_401:
	v_mad_u32_u24 v81, v80, s3, v115
	ds_read_b128 v[76:79], v81
	ds_read_b128 v[146:149], v81 offset:64
	ds_read_b128 v[228:231], v81 offset:128
	ds_read_b128 v[232:235], v81 offset:192
	v_add_u32_e32 v80, -16, v80
	s_waitcnt lgkmcnt(3)
	v_mfma_f32_16x16x32_bf16 v[134:137], v[76:79], v[0:3], 0
	v_mfma_f32_16x16x32_bf16 v[138:141], v[76:79], v[16:19], 0
	v_mfma_f32_16x16x32_bf16 v[142:145], v[76:79], v[32:35], 0
	v_mfma_f32_16x16x32_bf16 v[76:79], v[76:79], v[48:51], 0
	s_waitcnt lgkmcnt(2)
	v_mfma_f32_16x16x32_bf16 v[134:137], v[146:149], v[4:7], v[134:137]
	v_mfma_f32_16x16x32_bf16 v[138:141], v[146:149], v[20:23], v[138:141]
	v_mfma_f32_16x16x32_bf16 v[142:145], v[146:149], v[36:39], v[142:145]
	v_mfma_f32_16x16x32_bf16 v[76:79], v[146:149], v[52:55], v[76:79]
	s_waitcnt lgkmcnt(1)
	v_mfma_f32_16x16x32_bf16 v[134:137], v[228:231], v[8:11], v[134:137]
	v_mfma_f32_16x16x32_bf16 v[138:141], v[228:231], v[24:27], v[138:141]
	s_waitcnt lgkmcnt(0)
	v_mfma_f32_16x16x32_bf16 v[134:137], v[232:235], v[12:15], v[134:137]
	v_mfma_f32_16x16x32_bf16 v[142:145], v[228:231], v[40:43], v[142:145]
	v_mfma_f32_16x16x32_bf16 v[76:79], v[228:231], v[56:59], v[76:79]
	s_nop 5
	v_fmamk_f32 v81, v134, 0xbfb8aa3b, v125
	s_nop 0
	v_exp_f32_e32 v81, v81
	v_mfma_f32_16x16x32_bf16 v[142:145], v[232:235], v[44:47], v[142:145]
	v_add_f32_e32 v81, 1.0, v81
	v_rcp_f32_e32 v81, v81
	v_mfma_f32_16x16x32_bf16 v[138:141], v[232:235], v[28:31], v[138:141]
	s_nop 4
	v_fmamk_f32 v82, v142, 0xbfb8aa3b, v126
	s_nop 0
	v_mul_f32_e32 v81, v81, v127
	s_nop 0
	v_exp_f32_e32 v83, v81
	v_exp_f32_e32 v82, v82
	v_fmamk_f32 v97, v143, 0xbfb8aa3b, v126
	v_fma_f32 v81, -v83, v83, 1.0
	v_add_f32_e32 v82, 1.0, v82
	v_max_f32_e32 v81, 0, v81
	v_rcp_f32_e32 v82, v82
	v_sqrt_f32_e32 v81, v81
	v_exp_f32_e32 v97, v97
	v_mfma_f32_16x16x32_bf16 v[76:79], v[232:235], v[60:63], v[76:79]
	v_mul_f32_e32 v134, v82, v81
	v_fmamk_f32 v82, v135, 0xbfb8aa3b, v125
	s_nop 0
	v_exp_f32_e32 v82, v82
	v_add_f32_e32 v97, 1.0, v97
	v_rcp_f32_e32 v97, v97
	v_add_u32_e32 v81, s4, v122
	v_add_f32_e32 v82, 1.0, v82
	v_rcp_f32_e32 v82, v82
	ds_read2_b32 v[146:147], v81 offset1:16
	ds_read2_b32 v[150:151], v81 offset0:132 offset1:148
	v_add_u32_e32 v81, 0x400, v81
	v_mul_f32_e32 v82, v82, v127
	v_exp_f32_e32 v143, v82
	ds_read2_b32 v[156:157], v81 offset0:140 offset1:156
	ds_read2_b32 v[154:155], v81 offset0:8 offset1:24
	s_waitcnt lgkmcnt(2)
	v_mov_b32_e32 v142, v150
	v_fma_f32 v82, -v143, v143, 1.0
	v_max_f32_e32 v82, 0, v82
	v_sqrt_f32_e32 v82, v82
	s_waitcnt lgkmcnt(0)
	v_mov_b32_e32 v152, v154
	v_fmamk_f32 v76, v76, 0xbfb8aa3b, v129
	s_nop 0
	v_mul_f32_e32 v148, v97, v82
	v_fmamk_f32 v82, v136, 0xbfb8aa3b, v125
	s_nop 0
	v_exp_f32_e32 v82, v82
	v_fmamk_f32 v97, v144, 0xbfb8aa3b, v126
	s_nop 0
	v_exp_f32_e32 v97, v97
	v_add_f32_e32 v82, 1.0, v82
	v_rcp_f32_e32 v82, v82
	v_exp_f32_e32 v76, v76
	v_add_f32_e32 v97, 1.0, v97
	v_rcp_f32_e32 v97, v97
	v_mul_f32_e32 v82, v82, v127
	v_exp_f32_e32 v153, v82
	v_add_f32_e32 v76, 1.0, v76
	v_rcp_f32_e32 v76, v76
	v_fmamk_f32 v77, v77, 0xbfb8aa3b, v129
	v_fma_f32 v82, -v153, v153, 1.0
	v_max_f32_e32 v82, 0, v82
	v_sqrt_f32_e32 v82, v82
	v_exp_f32_e32 v77, v77
	v_fmamk_f32 v78, v78, 0xbfb8aa3b, v129
	v_mul_f32_e32 v136, v97, v82
	v_fmamk_f32 v82, v137, 0xbfb8aa3b, v125
	v_exp_f32_e32 v82, v82
	v_fmamk_f32 v97, v145, 0xbfb8aa3b, v126
	v_exp_f32_e32 v97, v97
	v_add_f32_e32 v82, 1.0, v82
	v_rcp_f32_e32 v82, v82
	v_mov_b32_e32 v145, v156
	v_add_f32_e32 v97, 1.0, v97
	v_rcp_f32_e32 v97, v97
	v_mul_f32_e32 v82, v82, v127
	v_exp_f32_e32 v144, v82
	v_add_f32_e32 v77, 1.0, v77
	v_rcp_f32_e32 v77, v77
	v_fma_f32 v82, -v144, v144, 1.0
	v_max_f32_e32 v82, 0, v82
	v_sqrt_f32_e32 v82, v82
	v_mul_f32_e32 v81, v144, v153
	v_mul_f32_e32 v81, v143, v81
	v_mul_f32_e32 v81, v83, v81
	v_mul_f32_e32 v97, v97, v82
	v_mul_f32_e32 v82, 0, v144
	v_pk_fma_f32 v[158:159], v[144:145], v[96:97], v[82:83] op_sel_hi:[1,1,0]
	v_mul_f32_e32 v82, v154, v136
	v_mov_b32_e32 v137, v159
	v_pk_fma_f32 v[136:137], v[152:153], v[136:137], v[82:83] op_sel_hi:[1,1,0]
	v_mul_f32_e32 v82, v150, v148
	v_mov_b32_e32 v149, v137
	v_pk_fma_f32 v[136:137], v[142:143], v[148:149], v[82:83] op_sel_hi:[1,1,0]
	v_mov_b32_e32 v82, v146
	v_mov_b32_e32 v135, v137
	v_mul_f32_e32 v136, v83, v137
	v_pk_fma_f32 v[134:135], v[82:83], v[134:135], v[136:137] op_sel_hi:[1,1,0]
	ds_bpermute_b32 v82, v132, v81
	ds_bpermute_b32 v142, v131, v81
	ds_bpermute_b32 v146, v133, v81
	ds_bpermute_b32 v150, v93, v81
	v_fmamk_f32 v81, v138, 0xbfb8aa3b, v130
	v_exp_f32_e32 v81, v81
	v_exp_f32_e32 v78, v78
	v_fmamk_f32 v79, v79, 0xbfb8aa3b, v129
	v_add_f32_e32 v81, 1.0, v81
	v_rcp_f32_e32 v81, v81
	v_add_f32_e32 v78, 1.0, v78
	v_rcp_f32_e32 v78, v78
	v_exp_f32_e32 v79, v79
	v_mul_f32_e32 v81, v81, v128
	v_exp_f32_e32 v153, v81
	v_add_f32_e32 v79, 1.0, v79
	v_rcp_f32_e32 v79, v79
	v_mov_b32_e32 v97, v157
	v_fma_f32 v81, -v153, v153, 1.0
	v_max_f32_e32 v81, 0, v81
	v_sqrt_f32_e32 v81, v81
	v_mov_b32_e32 v158, v155
	v_mov_b32_e32 v152, v147
	ds_bpermute_b32 v136, v132, v134
	v_mul_f32_e32 v76, v76, v81
	v_fmamk_f32 v81, v139, 0xbfb8aa3b, v130
	v_exp_f32_e32 v81, v81
	ds_bpermute_b32 v144, v131, v134
	ds_bpermute_b32 v148, v133, v134
	ds_bpermute_b32 v134, v93, v134
	v_add_f32_e32 v81, 1.0, v81
	v_rcp_f32_e32 v81, v81
	s_addk_i32 s4, 0xdf00
	s_cmpk_lg_i32 s4, 0x6700
	v_mul_f32_e32 v81, v81, v128
	s_nop 0
	v_exp_f32_e32 v139, v81
	s_nop 0
	v_fma_f32 v81, -v139, v139, 1.0
	v_max_f32_e32 v81, 0, v81
	v_sqrt_f32_e32 v81, v81
	s_nop 0
	v_mul_f32_e32 v154, v77, v81
	v_fmamk_f32 v77, v140, 0xbfb8aa3b, v130
	s_nop 0
	v_exp_f32_e32 v77, v77
	s_nop 0
	v_add_f32_e32 v77, 1.0, v77
	v_rcp_f32_e32 v77, v77
	s_nop 0
	v_mul_f32_e32 v77, v77, v128
	s_nop 0
	v_exp_f32_e32 v159, v77
	s_nop 0
	v_fma_f32 v77, -v159, v159, 1.0
	v_max_f32_e32 v77, 0, v77
	v_sqrt_f32_e32 v77, v77
	s_nop 0
	v_mul_f32_e32 v78, v78, v77
	v_fmamk_f32 v77, v141, 0xbfb8aa3b, v130
	s_nop 0
	v_exp_f32_e32 v77, v77
	s_nop 0
	v_add_f32_e32 v77, 1.0, v77
	v_rcp_f32_e32 v77, v77
	s_nop 0
	v_mul_f32_e32 v77, v77, v128
	s_nop 0
	v_exp_f32_e32 v140, v77
	s_nop 0
	v_fma_f32 v77, -v140, v140, 1.0
	v_max_f32_e32 v77, 0, v77
	v_sqrt_f32_e32 v77, v77
	v_mul_f32_e32 v138, 0, v140
	v_mul_f32_e32 v141, v79, v77
	v_pk_fma_f32 v[156:157], v[140:141], v[96:97], v[138:139] op_sel_hi:[1,1,0]
	v_mul_f32_e32 v138, v78, v155
	v_mov_b32_e32 v79, v157
	v_pk_fma_f32 v[78:79], v[78:79], v[158:159], v[138:139] op_sel_hi:[1,1,0]
	v_mov_b32_e32 v138, v151
	v_mov_b32_e32 v155, v79
	v_mul_f32_e32 v78, v154, v151
	v_mul_f32_e32 v77, v140, v159
	v_pk_fma_f32 v[78:79], v[154:155], v[138:139], v[78:79] op_sel_hi:[1,1,0]
	v_mul_f32_e32 v81, v139, v77
	v_mov_b32_e32 v77, v79
	v_mul_f32_e32 v78, v79, v153
	v_pk_fma_f32 v[76:77], v[76:77], v[152:153], v[78:79] op_sel_hi:[1,1,0]
	ds_bpermute_b32 v137, v132, v76
	v_mul_f32_e32 v77, v153, v81
	ds_bpermute_b32 v83, v132, v77
	ds_bpermute_b32 v143, v131, v77
	ds_bpermute_b32 v145, v131, v76
	ds_bpermute_b32 v147, v133, v77
	ds_bpermute_b32 v149, v133, v76
	ds_bpermute_b32 v151, v93, v77
	ds_bpermute_b32 v135, v93, v76
	s_waitcnt lgkmcnt(6)
	v_pk_fma_f32 v[76:77], v[110:111], v[82:83], v[136:137]
	s_waitcnt lgkmcnt(4)
	v_pk_fma_f32 v[76:77], v[76:77], v[142:143], v[144:145]
	s_waitcnt lgkmcnt(2)
	v_pk_fma_f32 v[76:77], v[76:77], v[146:147], v[148:149]
	s_waitcnt lgkmcnt(0)
	v_pk_fma_f32 v[110:111], v[76:77], v[150:151], v[134:135]
	v_pk_mul_f32 v[76:77], v[82:83], v[142:143]
	s_nop 0
	v_pk_mul_f32 v[76:77], v[76:77], v[146:147]
	s_nop 0
	v_pk_mul_f32 v[76:77], v[76:77], v[150:151]
	s_nop 0
	v_pk_mul_f32 v[108:109], v[108:109], v[76:77]
	s_cbranch_scc1 .LBB0_401
	s_mov_b64 s[18:19], 0

.LBB0_405:
	v_add_u32_e32 v97, 0, v135
	v_add_u32_e32 v76, 0x10c00, v97
	ds_read_b128 v[76:79], v76
	v_add_u32_e32 v144, 0x10c40, v97
	ds_read_b128 v[144:147], v144
	v_add_u32_e32 v228, 0x10c80, v97
	ds_read_b128 v[228:231], v228
	v_add_u32_e32 v232, 0x10cc0, v97
	ds_read_b128 v[232:235], v232
	s_add_i32 s4, s4, -1
	v_add_u32_e32 v135, 0x1100, v135
	s_cmp_eq_u32 s4, 0
	s_waitcnt lgkmcnt(3)
	v_mfma_f32_16x16x32_bf16 v[80:83], v[76:79], v[0:3], 0
	v_mfma_f32_16x16x32_bf16 v[136:139], v[76:79], v[16:19], 0
	v_mfma_f32_16x16x32_bf16 v[140:143], v[76:79], v[32:35], 0
	v_mfma_f32_16x16x32_bf16 v[76:79], v[76:79], v[48:51], 0
	s_waitcnt lgkmcnt(2)
	v_mfma_f32_16x16x32_bf16 v[80:83], v[144:147], v[4:7], v[80:83]
	v_mfma_f32_16x16x32_bf16 v[136:139], v[144:147], v[20:23], v[136:139]
	v_mfma_f32_16x16x32_bf16 v[140:143], v[144:147], v[36:39], v[140:143]
	v_mfma_f32_16x16x32_bf16 v[76:79], v[144:147], v[52:55], v[76:79]
	s_waitcnt lgkmcnt(1)
	v_mfma_f32_16x16x32_bf16 v[80:83], v[228:231], v[8:11], v[80:83]
	v_mfma_f32_16x16x32_bf16 v[136:139], v[228:231], v[24:27], v[136:139]
	s_waitcnt lgkmcnt(0)
	v_mfma_f32_16x16x32_bf16 v[148:151], v[232:235], v[12:15], v[80:83]
	v_mfma_f32_16x16x32_bf16 v[140:143], v[228:231], v[40:43], v[140:143]
	v_mfma_f32_16x16x32_bf16 v[76:79], v[228:231], v[56:59], v[76:79]
	s_nop 5
	v_fmamk_f32 v97, v148, 0xbfb8aa3b, v125
	v_mfma_f32_16x16x32_bf16 v[80:83], v[232:235], v[28:31], v[136:139]
	s_nop 0
	v_exp_f32_e32 v97, v97
	v_mfma_f32_16x16x32_bf16 v[136:139], v[232:235], v[44:47], v[140:143]
	v_add_f32_e32 v97, 1.0, v97
	v_rcp_f32_e32 v97, v97
	s_nop 0
	v_fmamk_f32 v143, v149, 0xbfb8aa3b, v125
	s_nop 0
	v_exp_f32_e32 v143, v143
	s_nop 1
	v_fmamk_f32 v137, v137, 0xbfb8aa3b, v126
	s_nop 0
	v_exp_f32_e32 v137, v137
	v_add_f32_e32 v143, 1.0, v143
	v_rcp_f32_e32 v143, v143
	v_mfma_f32_16x16x32_bf16 v[76:79], v[232:235], v[60:63], v[76:79]
	v_add_f32_e32 v137, 1.0, v137
	v_rcp_f32_e32 v137, v137
	v_mul_f32_e32 v143, v143, v127
	v_exp_f32_e32 v143, v143
	v_fmamk_f32 v136, v136, 0xbfb8aa3b, v126
	v_exp_f32_e32 v136, v136
	v_fma_f32 v144, -v143, v143, 1.0
	v_max_f32_e32 v144, 0, v144
	v_sqrt_f32_e32 v144, v144
	v_mul_f32_e32 v97, v97, v127
	v_add_f32_e32 v136, 1.0, v136
	v_mul_f32_e32 v144, v137, v144
	v_fmamk_f32 v137, v150, 0xbfb8aa3b, v125
	v_exp_f32_e32 v137, v137
	v_fmamk_f32 v138, v138, 0xbfb8aa3b, v126
	v_rcp_f32_e32 v140, v136
	v_exp_f32_e32 v136, v97
	v_add_f32_e32 v137, 1.0, v137
	v_rcp_f32_e32 v137, v137
	v_exp_f32_e32 v138, v138
	v_fma_f32 v97, -v136, v136, 1.0
	v_mul_f32_e32 v137, v137, v127
	v_exp_f32_e32 v149, v137
	v_max_f32_e32 v97, 0, v97
	v_add_f32_e32 v138, 1.0, v138
	v_sqrt_f32_e32 v97, v97
	v_fma_f32 v137, -v149, v149, 1.0
	v_max_f32_e32 v137, 0, v137
	v_rcp_f32_e32 v138, v138
	v_sqrt_f32_e32 v137, v137
	v_add_u32_e32 v142, 0, v134
	v_mul_f32_e32 v97, v140, v97
	ds_read2_b32 v[140:141], v142 offset1:16
	ds_read2_b32 v[146:147], v142 offset0:132 offset1:148
	v_mul_f32_e32 v138, v138, v137
	v_add_u32_e32 v137, 0x400, v142
	v_fmamk_f32 v142, v151, 0xbfb8aa3b, v125
	v_exp_f32_e32 v142, v142
	v_fmamk_f32 v139, v139, 0xbfb8aa3b, v126
	v_exp_f32_e32 v139, v139
	v_add_f32_e32 v142, 1.0, v142
	v_rcp_f32_e32 v142, v142
	v_fmamk_f32 v80, v80, 0xbfb8aa3b, v130
	v_exp_f32_e32 v80, v80
	v_mul_f32_e32 v142, v142, v127
	v_exp_f32_e32 v151, v142
	v_add_f32_e32 v139, 1.0, v139
	v_rcp_f32_e32 v139, v139
	ds_read2_b32 v[152:153], v137 offset0:8 offset1:24
	v_fma_f32 v142, -v151, v151, 1.0
	v_max_f32_e32 v142, 0, v142
	v_sqrt_f32_e32 v142, v142
	ds_read2_b32 v[156:157], v137 offset0:140 offset1:156
	s_waitcnt lgkmcnt(3)
	v_mov_b32_e32 v137, v140
	v_mul_f32_e32 v140, 0, v136
	v_add_f32_e32 v80, 1.0, v80
	v_pk_fma_f32 v[158:159], v[136:137], v[96:97], v[140:141] op_sel_hi:[1,1,0]
	v_rcp_f32_e32 v80, v80
	v_mul_f32_e32 v154, v139, v142
	s_waitcnt lgkmcnt(2)
	v_mov_b32_e32 v142, v146
	v_mov_b32_e32 v145, v159
	v_mul_f32_e32 v140, v146, v144
	v_pk_fma_f32 v[144:145], v[142:143], v[144:145], v[140:141] op_sel_hi:[1,1,0]
	v_mul_f32_e32 v97, v136, v143
	s_waitcnt lgkmcnt(1)
	v_mov_b32_e32 v148, v152
	v_mov_b32_e32 v139, v145
	v_mul_f32_e32 v136, v152, v138
	v_pk_fma_f32 v[136:137], v[148:149], v[138:139], v[136:137] op_sel_hi:[1,1,0]
	v_mul_f32_e32 v80, v80, v128
	s_waitcnt lgkmcnt(0)
	v_mov_b32_e32 v150, v156
	v_mov_b32_e32 v155, v137
	v_mul_f32_e32 v136, v151, v137
	v_fmamk_f32 v76, v76, 0xbfb8aa3b, v129
	v_pk_fma_f32 v[136:137], v[150:151], v[154:155], v[136:137] op_sel_hi:[1,1,0]
	v_exp_f32_e32 v154, v80
	v_exp_f32_e32 v76, v76
	v_fmamk_f32 v77, v77, 0xbfb8aa3b, v129
	v_fma_f32 v80, -v154, v154, 1.0
	v_add_f32_e32 v76, 1.0, v76
	v_max_f32_e32 v80, 0, v80
	v_rcp_f32_e32 v76, v76
	v_sqrt_f32_e32 v80, v80
	v_exp_f32_e32 v77, v77
	v_fmamk_f32 v78, v78, 0xbfb8aa3b, v129
	v_mul_f32_e32 v155, v76, v80
	v_fmamk_f32 v76, v81, 0xbfb8aa3b, v130
	v_exp_f32_e32 v76, v76
	v_add_f32_e32 v77, 1.0, v77
	v_rcp_f32_e32 v80, v77
	v_exp_f32_e32 v78, v78
	v_add_f32_e32 v76, 1.0, v76
	v_rcp_f32_e32 v76, v76
	v_fmamk_f32 v79, v79, 0xbfb8aa3b, v129
	v_add_f32_e32 v78, 1.0, v78
	v_rcp_f32_e32 v78, v78
	v_mul_f32_e32 v76, v76, v128
	v_exp_f32_e32 v77, v76
	v_exp_f32_e32 v79, v79
	v_mul_f32_e32 v97, v149, v97
	v_fma_f32 v76, -v77, v77, 1.0
	v_max_f32_e32 v76, 0, v76
	v_sqrt_f32_e32 v76, v76
	v_add_f32_e32 v79, 1.0, v79
	v_rcp_f32_e32 v79, v79
	v_mul_f32_e32 v97, v151, v97
	v_mul_f32_e32 v80, v80, v76
	v_fmamk_f32 v76, v82, 0xbfb8aa3b, v130
	v_exp_f32_e32 v76, v76
	ds_bpermute_b32 v138, v93, v97
	ds_bpermute_b32 v142, v133, v97
	ds_bpermute_b32 v146, v131, v97
	v_add_f32_e32 v76, 1.0, v76
	v_rcp_f32_e32 v76, v76
	ds_bpermute_b32 v150, v132, v97
	v_mov_b32_e32 v97, v141
	v_mul_f32_e32 v82, v80, v147
	v_mul_f32_e32 v76, v76, v128
	v_exp_f32_e32 v159, v76
	v_mov_b32_e32 v158, v153
	ds_bpermute_b32 v140, v93, v136
	ds_bpermute_b32 v144, v133, v136
	v_fma_f32 v76, -v159, v159, 1.0
	v_max_f32_e32 v76, 0, v76
	v_sqrt_f32_e32 v76, v76
	ds_bpermute_b32 v148, v131, v136
	ds_bpermute_b32 v136, v132, v136
	v_add_u32_e32 v134, 0x2100, v134
	v_mul_f32_e32 v78, v78, v76
	v_fmamk_f32 v76, v83, 0xbfb8aa3b, v130
	s_nop 0
	v_exp_f32_e32 v76, v76
	s_nop 0
	v_add_f32_e32 v76, 1.0, v76
	v_rcp_f32_e32 v76, v76
	s_nop 0
	v_mul_f32_e32 v76, v76, v128
	s_nop 0
	v_exp_f32_e32 v83, v76
	s_nop 0
	v_fma_f32 v76, -v83, v83, 1.0
	v_max_f32_e32 v76, 0, v76
	v_sqrt_f32_e32 v76, v76
	s_nop 0
	v_mul_f32_e32 v152, v79, v76
	v_mul_f32_e32 v76, 0, v154
	v_pk_fma_f32 v[160:161], v[154:155], v[96:97], v[76:77] op_sel_hi:[1,1,0]
	v_mov_b32_e32 v76, v147
	v_mov_b32_e32 v81, v161
	v_pk_fma_f32 v[80:81], v[80:81], v[76:77], v[82:83] op_sel_hi:[1,1,0]
	v_mul_f32_e32 v76, v78, v153
	v_mov_b32_e32 v79, v81
	v_mul_f32_e32 v80, v154, v77
	v_pk_fma_f32 v[76:77], v[78:79], v[158:159], v[76:77] op_sel_hi:[1,1,0]
	v_mov_b32_e32 v82, v157
	v_mov_b32_e32 v153, v77
	v_mul_f32_e32 v76, v77, v83
	v_mul_f32_e32 v78, v159, v80
	v_pk_fma_f32 v[76:77], v[152:153], v[82:83], v[76:77] op_sel_hi:[1,1,0]
	ds_bpermute_b32 v141, v93, v76
	v_mul_f32_e32 v77, v83, v78
	ds_bpermute_b32 v139, v93, v77
	ds_bpermute_b32 v143, v133, v77
	ds_bpermute_b32 v145, v133, v76
	ds_bpermute_b32 v147, v131, v77
	ds_bpermute_b32 v149, v131, v76
	ds_bpermute_b32 v151, v132, v77
	ds_bpermute_b32 v137, v132, v76
	s_waitcnt lgkmcnt(6)
	v_pk_fma_f32 v[76:77], v[110:111], v[138:139], v[140:141]
	s_waitcnt lgkmcnt(4)
	v_pk_fma_f32 v[76:77], v[76:77], v[142:143], v[144:145]
	s_waitcnt lgkmcnt(2)
	v_pk_fma_f32 v[76:77], v[76:77], v[146:147], v[148:149]
	s_waitcnt lgkmcnt(0)
	v_pk_fma_f32 v[110:111], v[76:77], v[150:151], v[136:137]
	v_pk_mul_f32 v[76:77], v[138:139], v[142:143]
	s_nop 0
	v_pk_mul_f32 v[76:77], v[76:77], v[146:147]
	s_nop 0
	v_pk_mul_f32 v[76:77], v[76:77], v[150:151]
	s_nop 0
	v_pk_mul_f32 v[108:109], v[108:109], v[76:77]
	s_cbranch_scc0 .LBB0_405
